# scalar M0 for LDS-DMA issue in attention and in-proj k-loops (no VALU add + readfirstlane per piece)
# speedup vs baseline: 1.0533x; 1.0043x over previous
; template <int EPI>
; DI void gemm_tile(const GemmArgs& ga, const EpiArgs& ea, int m0, int n0, char* lds) {
;     ...
;   const int K = ga.K, nk = K >> 5;
;   float rowsum = 0.f;
;   if constexpr (EPI == EPI_INPROJ) rowsum = sum16(ea.rowss, m0 + tid);
;   const int prow = lane >> 2, pch = lane & 3;
;   const bf16_t* gsrc[6];
;   int ldsoff[6];
; #pragma unroll
;   for (int i = 0; i < 6; ++i) {
;     const int pi = w * 6 + i;
;     if (pi < 16) {
;       const int row = pi * 16 + prow;
;       gsrc[i] = ga.A + (size_t)(m0 + row) * ga.lda + swz64(row, pch) * 8;
;       ldsoff[i] = pi * 1024 + lane * 16;
;     } else {
;       const int row = (pi - 16) * 16 + prow;
;       gsrc[i] = ga.Bt + (size_t)(n0 + row) * K + swz64(row, pch) * 8;
;       ldsoff[i] = pi * 1024 + lane * 16;
;     }
;   }
;   auto dma = [&](int kt, int buf) {
;     const int k0 = kt << 5;
;     const int ac = ga.mix ? mixcol(k0) : k0;
;     char* base = lds + buf * 24576;
; #pragma unroll
;     for (int i = 0; i < 6; ++i) {
;       const int pi = w * 6 + i;
;       __builtin_amdgcn_global_load_lds((const unsigned*)(gsrc[i] + ((pi < 16) ? ac : k0)), (unsigned*)(base + ldsoff[i]), 16, 0, 0);
;     }
;   };
;   __syncthreads();
;   dma(0, 0);
;   if (nk > 1) dma(1, 1);
.LBB0_179:
	s_lshl_b32 s26, s8, 8
	v_mov_b32_e32 v167, v172
	s_lshl_b32 s23, s22, 7
	v_add_u32_e32 v2, s26, v167
	v_ashrrev_i32_e32 v3, 31, v2
	v_lshl_add_u64 v[2:3], v[2:3], 2, s[6:7]
	v_add_co_u32_e32 v4, vcc, 0x20000, v2
	v_ashrrev_i32_e32 v24, 6, v167
	s_nop 0
	v_addc_co_u32_e32 v5, vcc, 0, v3, vcc
	v_add_co_u32_e32 v6, vcc, 0x40000, v2
	v_mul_lo_u32 v26, v24, 6
	s_nop 0
	v_addc_co_u32_e32 v7, vcc, 0, v3, vcc
	v_add_co_u32_e32 v8, vcc, 0x60000, v2
	s_add_i32 s24, s23, 0xffffff00
	s_nop 0
	v_addc_co_u32_e32 v9, vcc, 0, v3, vcc
	v_add_co_u32_e32 v10, vcc, 0x80000, v2
	s_movk_i32 s9, 0x60
	s_nop 0
	v_addc_co_u32_e32 v11, vcc, 0, v3, vcc
	v_add_co_u32_e32 v12, vcc, 0xa0000, v2
	v_and_b32_e32 v143, 63, v167
	s_nop 0
	v_addc_co_u32_e32 v13, vcc, 0, v3, vcc
	v_add_co_u32_e32 v14, vcc, 0xc0000, v2
	v_mul_lo_u32 v31, v24, s9
	s_nop 0
	v_addc_co_u32_e32 v15, vcc, 0, v3, vcc
	v_add_co_u32_e32 v16, vcc, 0xe0000, v2
	s_movk_i32 s9, 0x1800
	s_nop 0
	v_addc_co_u32_e32 v17, vcc, 0, v3, vcc
	global_load_dword v146, v[2:3], off
	global_load_dword v147, v[4:5], off
	global_load_dword v156, v[6:7], off
	global_load_dword v157, v[8:9], off
	global_load_dword v158, v[10:11], off
	global_load_dword v159, v[12:13], off
	global_load_dword v160, v[14:15], off
	global_load_dword v161, v[16:17], off
	v_add_co_u32_e32 v4, vcc, 0x100000, v2
	v_lshlrev_b32_e32 v30, 4, v143
	s_nop 0
	v_addc_co_u32_e32 v5, vcc, 0, v3, vcc
	v_add_co_u32_e32 v6, vcc, 0x120000, v2
	v_add_u32_e32 v20, 2, v26
	s_nop 0
	v_addc_co_u32_e32 v7, vcc, 0, v3, vcc
	v_add_co_u32_e32 v8, vcc, 0x140000, v2
	v_add_u32_e32 v28, 3, v26
	s_nop 0
	v_addc_co_u32_e32 v9, vcc, 0, v3, vcc
	v_add_co_u32_e32 v10, vcc, 0x160000, v2
	v_lshl_or_b32 v188, v20, 10, v30
	s_nop 0
	v_addc_co_u32_e32 v11, vcc, 0, v3, vcc
	v_add_co_u32_e32 v12, vcc, 0x180000, v2
	v_lshl_or_b32 v189, v28, 10, v30
	s_nop 0
	v_addc_co_u32_e32 v13, vcc, 0, v3, vcc
	v_add_co_u32_e32 v14, vcc, 0x1a0000, v2
	v_add_u32_e32 v34, 16, v188
	s_nop 0
	v_addc_co_u32_e32 v15, vcc, 0, v3, vcc
	v_add_co_u32_e32 v16, vcc, 0x1c0000, v2
	v_add_u32_e32 v35, 16, v189
	s_nop 0
	v_addc_co_u32_e32 v17, vcc, 0, v3, vcc
	v_add_co_u32_e32 v2, vcc, 0x1e0000, v2
	v_and_b32_e32 v144, 1, v24
	s_nop 0
	v_addc_co_u32_e32 v3, vcc, 0, v3, vcc
	global_load_dword v162, v[4:5], off
	global_load_dword v163, v[6:7], off
	global_load_dword v164, v[8:9], off
	global_load_dword v165, v[10:11], off
	global_load_dword v166, v[12:13], off
	global_load_dword v168, v[14:15], off
	global_load_dword v169, v[16:17], off
	global_load_dword v145, v[2:3], off
	v_bfe_u32 v4, v167, 2, 4
	v_and_b32_e32 v0, 12, v4
	v_lshrrev_b32_e64 v0, v0, s34
	v_xor_b32_e32 v0, v0, v167
	v_lshlrev_b32_e32 v0, 4, v0
	v_and_b32_e32 v0, 48, v0
	v_or_b32_e32 v25, s24, v4
	v_lshl_add_u64 v[2:3], s[0:1], 0, v[0:1]
	v_or_b32_e32 v27, s26, v4
	v_lshl_add_u64 v[4:5], s[50:51], 0, v[0:1]
	v_cmp_gt_i32_e32 vcc, 3, v24
	v_or_b32_e32 v16, 1, v26
	v_mul_lo_u32 v12, v24, s9
	v_cndmask_b32_e32 v0, v25, v27, vcc
	v_cndmask_b32_e32 v7, v3, v5, vcc
	v_cndmask_b32_e32 v6, v2, v4, vcc
	v_cmp_gt_i32_e32 vcc, 16, v16
	v_or_b32_e32 v170, v12, v30
	v_add_u32_e32 v8, v0, v31
	v_cndmask_b32_e32 v32, v25, v27, vcc
	v_cndmask_b32_e32 v13, v3, v5, vcc
	v_cndmask_b32_e32 v12, v2, v4, vcc
	v_cmp_gt_i32_e32 vcc, 2, v24
	v_lshl_add_u32 v14, v16, 4, v32
	v_lshl_or_b32 v171, v16, 10, v30
	v_lshl_add_u32 v16, v20, 4, v0
	v_lshl_add_u32 v20, v28, 4, v0
	v_add_u32_e32 v0, 4, v26
	v_cndmask_b32_e32 v27, v25, v27, vcc
	v_cndmask_b32_e32 v2, v2, v4, vcc
	v_lshl_add_u32 v4, v0, 4, v27
	v_lshl_or_b32 v190, v0, 10, v30
	v_add_u32_e32 v0, 5, v26
	v_ashrrev_i32_e32 v9, 31, v8
	v_lshl_or_b32 v191, v0, 10, v30
	v_add_u32_e32 v30, 16, v170
	v_lshlrev_b64 v[8:9], 11, v[8:9]
	v_ashrrev_i32_e32 v15, 31, v14
	v_readfirstlane_b32 s24, v30
	v_readfirstlane_b32 s100, v170
	v_add_u32_e32 v33, 16, v171
	v_lshl_add_u64 v[10:11], v[6:7], 0, v[8:9]
	v_lshlrev_b64 v[14:15], 11, v[14:15]
	v_ashrrev_i32_e32 v17, 31, v16
	s_mov_b32 m0, s24
	v_readfirstlane_b32 s24, v33
	v_lshl_add_u64 v[14:15], v[12:13], 0, v[14:15]
	v_lshlrev_b64 v[16:17], 11, v[16:17]
	v_ashrrev_i32_e32 v21, 31, v20
	s_barrier
	global_load_lds_dwordx4 v[10:11], off
	s_mov_b32 m0, s24
	v_readfirstlane_b32 s24, v34
	v_lshl_add_u64 v[18:19], v[6:7], 0, v[16:17]
	v_lshlrev_b64 v[20:21], 11, v[20:21]
	v_cndmask_b32_e32 v3, v3, v5, vcc
	v_ashrrev_i32_e32 v5, 31, v4
	v_lshl_add_u32 v26, v0, 4, v27
	global_load_lds_dwordx4 v[14:15], off
	s_mov_b32 m0, s24
	v_readfirstlane_b32 s24, v35
	v_add_u32_e32 v36, 16, v190
	v_lshl_add_u64 v[22:23], v[6:7], 0, v[20:21]
	v_lshlrev_b64 v[4:5], 11, v[4:5]
	v_ashrrev_i32_e32 v27, 31, v26
	global_load_lds_dwordx4 v[18:19], off
	s_mov_b32 m0, s24
	v_readfirstlane_b32 s24, v36
	v_add_u32_e32 v37, 16, v191
	v_lshl_add_u64 v[24:25], v[2:3], 0, v[4:5]
	v_lshlrev_b64 v[26:27], 11, v[26:27]
	global_load_lds_dwordx4 v[22:23], off
	s_mov_b32 m0, s24
	v_readfirstlane_b32 s24, v37
	v_add_u32_e32 v30, 0x6000, v30
	v_lshl_add_u64 v[28:29], v[2:3], 0, v[26:27]
	global_load_lds_dwordx4 v[24:25], off
	s_mov_b32 m0, s24
	v_readfirstlane_b32 s24, v30
	global_load_lds_dwordx4 v[28:29], off
	v_lshl_add_u64 v[10:11], v[10:11], 0, 64
	s_mov_b32 m0, s24
	v_lshl_add_u64 v[6:7], v[6:7], 0, s[70:71]
	global_load_lds_dwordx4 v[10:11], off
	v_lshl_add_u64 v[10:11], v[14:15], 0, 64
	v_add_u32_e32 v14, 0x6000, v33
	v_lshl_add_u64 v[130:131], v[6:7], 0, v[8:9]
	v_readfirstlane_b32 s24, v14
	v_add_u32_e32 v14, 0x6000, v34
	s_mov_b32 m0, s24
	v_readfirstlane_b32 s24, v14
	v_add_u32_e32 v14, 0x6000, v35
	global_load_lds_dwordx4 v[10:11], off
	v_lshl_add_u64 v[10:11], v[18:19], 0, 64
	s_mov_b32 m0, s24
; template <int EPI>
; DI void gemm_tile(const GemmArgs& ga, const EpiArgs& ea, int m0, int n0, char* lds) {
;     ...
;   f32x4 acc[8][4];
; #pragma unroll
;   for (int i = 0; i < 8; ++i)
; #pragma unroll
;     for (int j = 0; j < 4; ++j) acc[i][j] = f32x4{0.f, 0.f, 0.f, 0.f};
;   const int K = ga.K, nk = K >> 5;
;   float rowsum = 0.f;
;   if constexpr (EPI == EPI_INPROJ) rowsum = sum16(ea.rowss, m0 + tid);
;   const int prow = lane >> 2, pch = lane & 3;
;   const bf16_t* gsrc[6];
;   int ldsoff[6];
; #pragma unroll
;   for (int i = 0; i < 6; ++i) {
;     const int pi = w * 6 + i;
;     if (pi < 16) {
;       const int row = pi * 16 + prow;
;       gsrc[i] = ga.A + (size_t)(m0 + row) * ga.lda + swz64(row, pch) * 8;
;       ldsoff[i] = pi * 1024 + lane * 16;
;     } else {
;       const int row = (pi - 16) * 16 + prow;
;       gsrc[i] = ga.Bt + (size_t)(n0 + row) * K + swz64(row, pch) * 8;
;       ldsoff[i] = pi * 1024 + lane * 16;
;     }
;   }
;   auto dma = [&](int kt, int buf) {
;     const int k0 = kt << 5;
;     const int ac = ga.mix ? mixcol(k0) : k0;
;     char* base = lds + buf * 24576;
; #pragma unroll
;     for (int i = 0; i < 6; ++i) {
;       const int pi = w * 6 + i;
;       __builtin_amdgcn_global_load_lds((const unsigned*)(gsrc[i] + ((pi < 16) ? ac : k0)), (unsigned*)(base + ldsoff[i]), 16, 0, 0);
;     }
;   };
;   __syncthreads();
;   dma(0, 0);
;   if (nk > 1) dma(1, 1);
	v_readfirstlane_b32 s24, v14
	v_add_u32_e32 v14, 0x6000, v36
	global_load_lds_dwordx4 v[10:11], off
	v_lshl_add_u64 v[10:11], v[22:23], 0, 64
	s_mov_b32 m0, s24
	v_readfirstlane_b32 s24, v14
	v_add_u32_e32 v14, 0x6000, v37
	global_load_lds_dwordx4 v[10:11], off
	v_lshl_add_u64 v[10:11], v[24:25], 0, 64
	s_mov_b32 m0, s24
	v_readfirstlane_b32 s24, v14
	global_load_lds_dwordx4 v[10:11], off
	v_lshl_add_u64 v[10:11], v[28:29], 0, 64
	s_mov_b32 m0, s24
	v_add_u32_e32 v8, v32, v31
	global_load_lds_dwordx4 v[10:11], off
	v_and_b32_e32 v11, 12, v167
	v_or_b32_e32 v8, 16, v8
	v_bfe_u32 v0, v167, 4, 2
	v_lshlrev_b32_e32 v10, 6, v167
	v_lshrrev_b32_e64 v11, v11, s34
	v_ashrrev_i32_e32 v9, 31, v8
	v_and_b32_e32 v10, 0xffffe000, v10
	v_bitop3_b32 v11, v11, v0, 3 bitop3:0x6c
	v_lshlrev_b64 v[8:9], 11, v[8:9]
	v_lshl_add_u64 v[2:3], v[2:3], 0, s[70:71]
	v_and_b32_e32 v142, 15, v167
	v_lshlrev_b32_e32 v192, 4, v11
	v_lshl_add_u64 v[8:9], v[12:13], 0, v[8:9]
	v_lshl_add_u64 v[138:139], v[2:3], 0, v[4:5]
	v_lshl_add_u64 v[140:141], v[2:3], 0, v[26:27]
	v_add_u32_e32 v193, 16, v10
	v_mov_b32_e32 v2, 0
	v_lshlrev_b32_e32 v194, 6, v142
	v_lshl_add_u32 v195, v144, 12, 16
	s_mov_b32 s8, 2
	s_mov_b32 s27, 0
	v_lshl_add_u64 v[132:133], v[8:9], 0, s[70:71]
	v_lshl_add_u64 v[134:135], v[6:7], 0, v[16:17]
	v_lshl_add_u64 v[136:137], v[6:7], 0, v[20:21]
	s_mov_b64 s[24:25], 0
	v_mov_b32_e32 v3, v2
	v_mov_b32_e32 v4, v2
	v_mov_b32_e32 v5, v2
	v_mov_b32_e32 v6, v2
	v_mov_b32_e32 v7, v2
	v_mov_b32_e32 v8, v2
	v_mov_b32_e32 v9, v2
	v_mov_b32_e32 v10, v2
	v_mov_b32_e32 v11, v2
	v_mov_b32_e32 v12, v2
	v_mov_b32_e32 v13, v2
	v_mov_b32_e32 v14, v2
	v_mov_b32_e32 v15, v2
	v_mov_b32_e32 v16, v2
	v_mov_b32_e32 v17, v2
	v_mov_b32_e32 v18, v2
	v_mov_b32_e32 v19, v2
	v_mov_b32_e32 v20, v2
	v_mov_b32_e32 v21, v2
	v_mov_b32_e32 v22, v2
	v_mov_b32_e32 v23, v2
	v_mov_b32_e32 v24, v2
	v_mov_b32_e32 v25, v2
	v_mov_b32_e32 v26, v2
	v_mov_b32_e32 v27, v2
	v_mov_b32_e32 v28, v2
	v_mov_b32_e32 v29, v2
	v_mov_b32_e32 v30, v2
	v_mov_b32_e32 v31, v2
	v_mov_b32_e32 v32, v2
	v_mov_b32_e32 v33, v2
	v_mov_b32_e32 v34, v2
	v_mov_b32_e32 v35, v2
	v_mov_b32_e32 v36, v2
	v_mov_b32_e32 v37, v2
	v_mov_b32_e32 v38, v2
	v_mov_b32_e32 v39, v2
	v_mov_b32_e32 v40, v2
	v_mov_b32_e32 v41, v2
	v_mov_b32_e32 v42, v2
	v_mov_b32_e32 v43, v2
	v_mov_b32_e32 v44, v2
	v_mov_b32_e32 v45, v2
	v_mov_b32_e32 v46, v2
	v_mov_b32_e32 v47, v2
	v_mov_b32_e32 v48, v2
	v_mov_b32_e32 v49, v2
	v_mov_b32_e32 v50, v2
	v_mov_b32_e32 v51, v2
	v_mov_b32_e32 v52, v2
	v_mov_b32_e32 v53, v2
	v_mov_b32_e32 v54, v2
	v_mov_b32_e32 v55, v2
	v_mov_b32_e32 v56, v2
	v_mov_b32_e32 v57, v2
	v_mov_b32_e32 v58, v2
	v_mov_b32_e32 v59, v2
	v_mov_b32_e32 v60, v2
	v_mov_b32_e32 v61, v2
	v_mov_b32_e32 v62, v2
	v_mov_b32_e32 v63, v2
	v_mov_b32_e32 v64, v2
	v_mov_b32_e32 v65, v2
	v_mov_b32_e32 v66, v2
	v_mov_b32_e32 v67, v2
	v_mov_b32_e32 v68, v2
	v_mov_b32_e32 v69, v2
	v_mov_b32_e32 v70, v2
	v_mov_b32_e32 v71, v2
	v_mov_b32_e32 v72, v2
	v_mov_b32_e32 v73, v2
	v_mov_b32_e32 v74, v2
	v_mov_b32_e32 v75, v2
	v_mov_b32_e32 v76, v2
	v_mov_b32_e32 v77, v2
	v_mov_b32_e32 v86, v2
	v_mov_b32_e32 v87, v2
	v_mov_b32_e32 v88, v2
	v_mov_b32_e32 v89, v2
	v_mov_b32_e32 v98, v2
	v_mov_b32_e32 v99, v2
	v_mov_b32_e32 v100, v2
	v_mov_b32_e32 v101, v2
	v_mov_b32_e32 v106, v2
	v_mov_b32_e32 v107, v2
	v_mov_b32_e32 v108, v2
	v_mov_b32_e32 v109, v2
	v_mov_b32_e32 v114, v2
	v_mov_b32_e32 v115, v2
	v_mov_b32_e32 v116, v2
	v_mov_b32_e32 v117, v2
	v_mov_b32_e32 v118, v2
	v_mov_b32_e32 v119, v2
	v_mov_b32_e32 v120, v2
	v_mov_b32_e32 v121, v2
	v_mov_b32_e32 v122, v2
	v_mov_b32_e32 v123, v2
	v_mov_b32_e32 v124, v2
	v_mov_b32_e32 v125, v2
	v_mov_b32_e32 v126, v2
	v_mov_b32_e32 v127, v2
	v_mov_b32_e32 v128, v2
	v_mov_b32_e32 v129, v2
	v_mov_b32_e32 v78, v2
	v_mov_b32_e32 v79, v2
	v_mov_b32_e32 v80, v2
	v_mov_b32_e32 v81, v2
	v_mov_b32_e32 v82, v2
	v_mov_b32_e32 v83, v2
	v_mov_b32_e32 v84, v2
	v_mov_b32_e32 v85, v2
	v_mov_b32_e32 v90, v2
	v_mov_b32_e32 v91, v2
	v_mov_b32_e32 v92, v2
	v_mov_b32_e32 v93, v2
	v_mov_b32_e32 v94, v2
	v_mov_b32_e32 v95, v2
	v_mov_b32_e32 v96, v2
	v_mov_b32_e32 v97, v2
	v_mov_b32_e32 v102, v2
	v_mov_b32_e32 v103, v2
	v_mov_b32_e32 v104, v2
	v_mov_b32_e32 v105, v2
	v_mov_b32_e32 v110, v2
	v_mov_b32_e32 v111, v2
	v_mov_b32_e32 v112, v2
	v_mov_b32_e32 v113, v2
	v_or_b32_e32 v196, v194, v192
	v_mov_b32_e32 v197, v193
	v_mov_b32_e32 v198, v195
; #define MFMA16(a, b, c) __builtin_amdgcn_mfma_f32_16x16x32_bf16((a), (b), (c), 0, 0, 0)
; template <int EPI>
; DI void gemm_tile(const GemmArgs& ga, const EpiArgs& ea, int m0, int n0, char* lds) {
;     ...
;   for (int kt = 0; kt < nk; ++kt) {
;     if (kt + 1 < nk) asm volatile("s_waitcnt vmcnt(6)" ::: "memory");
;     else asm volatile("s_waitcnt vmcnt(0)" ::: "memory");
;     __builtin_amdgcn_s_barrier();
;     const char* Ab = lds + (kt % 3) * 24576 + wm * 128 * 64;
;     const char* Bb = lds + (kt % 3) * 24576 + 16384 + wn * 64 * 64;
;     bf16x8 af[8], bfr[4];
;     const int ch = swz64(c16, quad) << 4;
; #pragma unroll
;     for (int nt = 0; nt < 4; ++nt) bfr[nt] = *(const bf16x8*)(Bb + (nt * 16 + c16) * 64 + ch);
; #pragma unroll
;     for (int mt = 0; mt < 2; ++mt) af[mt] = *(const bf16x8*)(Ab + (mt * 16 + c16) * 64 + ch);
;     __builtin_amdgcn_sched_barrier(0);
;     if (kt + 2 < nk) dma(kt + 2, (kt + 2) % 3);
;     __builtin_amdgcn_sched_barrier(0);
; #pragma unroll
;     for (int g = 0; g < 4; ++g) {
;       if (g < 3) {
; #pragma unroll
;         for (int mt = 2 * g + 2; mt < 2 * g + 4; ++mt) af[mt] = *(const bf16x8*)(Ab + (mt * 16 + c16) * 64 + ch);
;       }
; #pragma unroll
;       for (int mt = 2 * g; mt < 2 * g + 2; ++mt)
; #pragma unroll
;         for (int nt = 0; nt < 4; ++nt) acc[mt][nt] = MFMA16(bfr[nt], af[mt], acc[mt][nt]);
;       __builtin_amdgcn_sched_barrier(0);
;     }
.LBB0_180:
	s_mul_hi_u32 s28, s27, 0xaaaaaaab
	s_lshr_b32 s28, s28, 1
	s_mul_i32 s28, s28, 0xfffee000
	v_or_b32_e32 v199, s28, v196
	v_add_u32_e32 v212, v198, v199
	s_waitcnt vmcnt(6)
	s_barrier
	v_add_u32_e32 v199, v197, v199
	ds_read_b128 v[200:203], v212 offset:16384
	ds_read_b128 v[204:207], v212 offset:17408
	ds_read_b128 v[208:211], v212 offset:18432
	ds_read_b128 v[212:215], v212 offset:19456
	ds_read_b128 v[216:219], v199
	ds_read_b128 v[220:223], v199 offset:1024
	s_add_i32 s27, s27, 1
	s_mul_i32 s28, s8, 0xab
	s_bfe_u32 s28, s28, 0x70009
	s_mul_i32 s28, s28, 3
	s_sub_i32 s28, s8, s28
	s_and_b32 s28, s28, 0xff
	s_mulk_i32 s28, 0x6000
	s_add_i32 s28, s28, 16
	s_add_i32 s29, s28, s100
	s_mov_b32 m0, s29
	v_lshl_add_u64 v[224:225], v[130:131], 0, s[24:25]
	global_load_lds_dwordx4 v[224:225], off
	s_add_i32 m0, s29, 0x400
	v_lshl_add_u64 v[224:225], v[132:133], 0, s[24:25]
	global_load_lds_dwordx4 v[224:225], off
	s_add_i32 m0, s29, 0x800
	v_lshl_add_u64 v[224:225], v[134:135], 0, s[24:25]
	global_load_lds_dwordx4 v[224:225], off
	s_add_i32 m0, s29, 0xc00
	v_lshl_add_u64 v[224:225], v[136:137], 0, s[24:25]
	global_load_lds_dwordx4 v[224:225], off
	s_add_i32 m0, s29, 0x1000
	v_lshl_add_u64 v[224:225], v[138:139], 0, s[24:25]
	global_load_lds_dwordx4 v[224:225], off
	s_add_i32 m0, s29, 0x1400
	v_lshl_add_u64 v[224:225], v[140:141], 0, s[24:25]
	global_load_lds_dwordx4 v[224:225], off
	s_waitcnt lgkmcnt(0)
	v_mfma_f32_16x16x32_bf16 v[126:129], v[200:203], v[216:219], v[126:129]
	v_mfma_f32_16x16x32_bf16 v[122:125], v[204:207], v[216:219], v[122:125]
	v_mfma_f32_16x16x32_bf16 v[118:121], v[208:211], v[216:219], v[118:121]
	v_mfma_f32_16x16x32_bf16 v[114:117], v[212:215], v[216:219], v[114:117]
	ds_read_b128 v[216:219], v199 offset:2048
	ds_read_b128 v[224:227], v199 offset:3072
	v_mfma_f32_16x16x32_bf16 v[106:109], v[200:203], v[220:223], v[106:109]
	v_mfma_f32_16x16x32_bf16 v[98:101], v[204:207], v[220:223], v[98:101]
	v_mfma_f32_16x16x32_bf16 v[86:89], v[208:211], v[220:223], v[86:89]
	v_mfma_f32_16x16x32_bf16 v[74:77], v[212:215], v[220:223], v[74:77]
	s_waitcnt lgkmcnt(0)
	v_mfma_f32_16x16x32_bf16 v[70:73], v[200:203], v[216:219], v[70:73]
	v_mfma_f32_16x16x32_bf16 v[66:69], v[204:207], v[216:219], v[66:69]
	v_mfma_f32_16x16x32_bf16 v[62:65], v[208:211], v[216:219], v[62:65]
	v_mfma_f32_16x16x32_bf16 v[58:61], v[212:215], v[216:219], v[58:61]
	ds_read_b128 v[216:219], v199 offset:4096
	ds_read_b128 v[220:223], v199 offset:5120
	v_mfma_f32_16x16x32_bf16 v[54:57], v[200:203], v[224:227], v[54:57]
	v_mfma_f32_16x16x32_bf16 v[50:53], v[204:207], v[224:227], v[50:53]
	v_mfma_f32_16x16x32_bf16 v[46:49], v[208:211], v[224:227], v[46:49]
	v_mfma_f32_16x16x32_bf16 v[42:45], v[212:215], v[224:227], v[42:45]
	s_waitcnt lgkmcnt(0)
	v_mfma_f32_16x16x32_bf16 v[38:41], v[200:203], v[216:219], v[38:41]
	v_mfma_f32_16x16x32_bf16 v[34:37], v[204:207], v[216:219], v[34:37]
	v_mfma_f32_16x16x32_bf16 v[30:33], v[208:211], v[216:219], v[30:33]
	v_mfma_f32_16x16x32_bf16 v[26:29], v[212:215], v[216:219], v[26:29]
	ds_read_b128 v[216:219], v199 offset:6144
	ds_read_b128 v[224:227], v199 offset:7168
	v_mfma_f32_16x16x32_bf16 v[22:25], v[200:203], v[220:223], v[22:25]
	v_mfma_f32_16x16x32_bf16 v[18:21], v[204:207], v[220:223], v[18:21]
	v_mfma_f32_16x16x32_bf16 v[14:17], v[208:211], v[220:223], v[14:17]
	v_mfma_f32_16x16x32_bf16 v[10:13], v[212:215], v[220:223], v[10:13]
	s_waitcnt lgkmcnt(0)
	v_mfma_f32_16x16x32_bf16 v[6:9], v[200:203], v[216:219], v[6:9]
	v_mfma_f32_16x16x32_bf16 v[2:5], v[204:207], v[216:219], v[2:5]
	v_mfma_f32_16x16x32_bf16 v[78:81], v[208:211], v[216:219], v[78:81]
	v_mfma_f32_16x16x32_bf16 v[82:85], v[212:215], v[216:219], v[82:85]
	v_mfma_f32_16x16x32_bf16 v[90:93], v[200:203], v[224:227], v[90:93]
	v_mfma_f32_16x16x32_bf16 v[94:97], v[204:207], v[224:227], v[94:97]
	v_mfma_f32_16x16x32_bf16 v[102:105], v[208:211], v[224:227], v[102:105]
	v_mfma_f32_16x16x32_bf16 v[110:113], v[212:215], v[224:227], v[110:113]
	s_add_i32 s8, s8, 1
	s_add_u32 s24, s24, 64
	s_addc_u32 s25, s25, 0
	v_add_u32_e32 v198, 0x6000, v198
	s_cmpk_eq_i32 s24, 0x780
	v_add_u32_e32 v197, 0x6000, v197
	s_cbranch_scc0 .LBB0_180
	s_waitcnt vmcnt(0)
	v_add_f32_e32 v130, 0, v146
	v_add_f32_e32 v130, v130, v147
	v_add_f32_e32 v130, v130, v156
	v_add_f32_e32 v130, v130, v157
	v_add_f32_e32 v130, v130, v158
	v_add_f32_e32 v130, v130, v159
	v_add_f32_e32 v130, v130, v160
	v_add_f32_e32 v130, v130, v161
	v_add_f32_e32 v130, v130, v162
	v_add_f32_e32 v130, v130, v163
	v_add_f32_e32 v130, v130, v164
	v_add_f32_e32 v130, v130, v165
	v_add_f32_e32 v130, v130, v166
	v_add_f32_e32 v130, v130, v168
	v_add3_u32 v147, v195, v192, v194
	v_add_f32_e32 v146, v130, v169
	s_waitcnt vmcnt(6)
	s_barrier
; #define MFMA16(a, b, c) __builtin_amdgcn_mfma_f32_16x16x32_bf16((a), (b), (c), 0, 0, 0)
; template <int EPI>
; DI void gemm_tile(const GemmArgs& ga, const EpiArgs& ea, int m0, int n0, char* lds) {
;     ...
;   for (int kt = 0; kt < nk; ++kt) {
;     if (kt + 1 < nk) asm volatile("s_waitcnt vmcnt(6)" ::: "memory");
;     else asm volatile("s_waitcnt vmcnt(0)" ::: "memory");
;     __builtin_amdgcn_s_barrier();
;     const char* Ab = lds + (kt % 3) * 24576 + wm * 128 * 64;
;     const char* Bb = lds + (kt % 3) * 24576 + 16384 + wn * 64 * 64;
;     bf16x8 af[8], bfr[4];
;     const int ch = swz64(c16, quad) << 4;
; #pragma unroll
;     for (int nt = 0; nt < 4; ++nt) bfr[nt] = *(const bf16x8*)(Bb + (nt * 16 + c16) * 64 + ch);
; #pragma unroll
;     for (int mt = 0; mt < 2; ++mt) af[mt] = *(const bf16x8*)(Ab + (mt * 16 + c16) * 64 + ch);
;     __builtin_amdgcn_sched_barrier(0);
;     if (kt + 2 < nk) dma(kt + 2, (kt + 2) % 3);
;     __builtin_amdgcn_sched_barrier(0);
; #pragma unroll
;     for (int g = 0; g < 4; ++g) {
;       if (g < 3) {
; #pragma unroll
;         for (int mt = 2 * g + 2; mt < 2 * g + 4; ++mt) af[mt] = *(const bf16x8*)(Ab + (mt * 16 + c16) * 64 + ch);
;       }
; #pragma unroll
;       for (int mt = 2 * g; mt < 2 * g + 2; ++mt)
; #pragma unroll
;         for (int nt = 0; nt < 4; ++nt) acc[mt][nt] = MFMA16(bfr[nt], af[mt], acc[mt][nt]);
;       __builtin_amdgcn_sched_barrier(0);
;     }
	ds_read_b128 v[130:133], v147 offset:16384
	ds_read_b128 v[134:137], v147 offset:17408
	ds_read_b128 v[138:141], v147 offset:18432
	ds_read_b128 v[156:159], v147 offset:19456
	v_add3_u32 v164, v193, v192, v194
	ds_read_b128 v[160:163], v164
	ds_read_b128 v[168:171], v164 offset:1024
	s_waitcnt lgkmcnt(1)
	v_mfma_f32_16x16x32_bf16 v[126:129], v[130:133], v[160:163], v[126:129]
	v_mfma_f32_16x16x32_bf16 v[122:125], v[134:137], v[160:163], v[122:125]
	v_mfma_f32_16x16x32_bf16 v[118:121], v[138:141], v[160:163], v[118:121]
	v_mfma_f32_16x16x32_bf16 v[114:117], v[156:159], v[160:163], v[114:117]
	ds_read_b128 v[160:163], v164 offset:2048
	ds_read_b128 v[188:191], v164 offset:3072
	s_waitcnt lgkmcnt(2)
	v_mfma_f32_16x16x32_bf16 v[106:109], v[130:133], v[168:171], v[106:109]
	v_mfma_f32_16x16x32_bf16 v[98:101], v[134:137], v[168:171], v[98:101]
	v_mfma_f32_16x16x32_bf16 v[86:89], v[138:141], v[168:171], v[86:89]
	v_mfma_f32_16x16x32_bf16 v[74:77], v[156:159], v[168:171], v[74:77]
	s_waitcnt lgkmcnt(1)
	v_mfma_f32_16x16x32_bf16 v[70:73], v[130:133], v[160:163], v[70:73]
	v_mfma_f32_16x16x32_bf16 v[66:69], v[134:137], v[160:163], v[66:69]
	v_mfma_f32_16x16x32_bf16 v[62:65], v[138:141], v[160:163], v[62:65]
	v_mfma_f32_16x16x32_bf16 v[58:61], v[156:159], v[160:163], v[58:61]
	ds_read_b128 v[160:163], v164 offset:4096
	ds_read_b128 v[168:171], v164 offset:5120
	s_waitcnt lgkmcnt(2)
	v_mfma_f32_16x16x32_bf16 v[54:57], v[130:133], v[188:191], v[54:57]
	v_mfma_f32_16x16x32_bf16 v[50:53], v[134:137], v[188:191], v[50:53]
	v_mfma_f32_16x16x32_bf16 v[46:49], v[138:141], v[188:191], v[46:49]
	v_mfma_f32_16x16x32_bf16 v[42:45], v[156:159], v[188:191], v[42:45]
	s_waitcnt lgkmcnt(1)
	v_mfma_f32_16x16x32_bf16 v[38:41], v[130:133], v[160:163], v[38:41]
	v_mfma_f32_16x16x32_bf16 v[34:37], v[134:137], v[160:163], v[34:37]
	v_mfma_f32_16x16x32_bf16 v[30:33], v[138:141], v[160:163], v[30:33]
	v_mfma_f32_16x16x32_bf16 v[26:29], v[156:159], v[160:163], v[26:29]
	ds_read_b128 v[160:163], v164 offset:6144
	ds_read_b128 v[188:191], v164 offset:7168
	s_waitcnt lgkmcnt(2)
	v_mfma_f32_16x16x32_bf16 v[22:25], v[130:133], v[168:171], v[22:25]
	v_mfma_f32_16x16x32_bf16 v[18:21], v[134:137], v[168:171], v[18:21]
	v_mfma_f32_16x16x32_bf16 v[14:17], v[138:141], v[168:171], v[14:17]
	v_mfma_f32_16x16x32_bf16 v[10:13], v[156:159], v[168:171], v[10:13]
	s_waitcnt lgkmcnt(1)
	v_mfma_f32_16x16x32_bf16 v[6:9], v[130:133], v[160:163], v[6:9]
	v_mfma_f32_16x16x32_bf16 v[2:5], v[134:137], v[160:163], v[2:5]
	v_mfma_f32_16x16x32_bf16 v[168:171], v[138:141], v[160:163], v[78:81]
	s_waitcnt lgkmcnt(0)
	v_mfma_f32_16x16x32_bf16 v[134:137], v[134:137], v[188:191], v[94:97]
	v_mfma_f32_16x16x32_bf16 v[138:141], v[138:141], v[188:191], v[102:105]
	v_mfma_f32_16x16x32_bf16 v[160:163], v[156:159], v[160:163], v[82:85]
	v_mfma_f32_16x16x32_bf16 v[130:133], v[130:133], v[188:191], v[90:93]
	v_mfma_f32_16x16x32_bf16 v[156:159], v[156:159], v[188:191], v[110:113]
	s_waitcnt vmcnt(0)
	s_barrier
; #define MFMA16(a, b, c) __builtin_amdgcn_mfma_f32_16x16x32_bf16((a), (b), (c), 0, 0, 0)
; template <int EPI>
; DI void gemm_tile(const GemmArgs& ga, const EpiArgs& ea, int m0, int n0, char* lds) {
;     ...
;   for (int kt = 0; kt < nk; ++kt) {
;     if (kt + 1 < nk) asm volatile("s_waitcnt vmcnt(6)" ::: "memory");
;     else asm volatile("s_waitcnt vmcnt(0)" ::: "memory");
;     __builtin_amdgcn_s_barrier();
;     const char* Ab = lds + (kt % 3) * 24576 + wm * 128 * 64;
;     const char* Bb = lds + (kt % 3) * 24576 + 16384 + wn * 64 * 64;
;     bf16x8 af[8], bfr[4];
;     const int ch = swz64(c16, quad) << 4;
; #pragma unroll
;     for (int nt = 0; nt < 4; ++nt) bfr[nt] = *(const bf16x8*)(Bb + (nt * 16 + c16) * 64 + ch);
; #pragma unroll
;     for (int mt = 0; mt < 2; ++mt) af[mt] = *(const bf16x8*)(Ab + (mt * 16 + c16) * 64 + ch);
;     __builtin_amdgcn_sched_barrier(0);
;     if (kt + 2 < nk) dma(kt + 2, (kt + 2) % 3);
;     __builtin_amdgcn_sched_barrier(0);
; #pragma unroll
;     for (int g = 0; g < 4; ++g) {
;       if (g < 3) {
; #pragma unroll
;         for (int mt = 2 * g + 2; mt < 2 * g + 4; ++mt) af[mt] = *(const bf16x8*)(Ab + (mt * 16 + c16) * 64 + ch);
;       }
; #pragma unroll
;       for (int mt = 2 * g; mt < 2 * g + 2; ++mt)
; #pragma unroll
;         for (int nt = 0; nt < 4; ++nt) acc[mt][nt] = MFMA16(bfr[nt], af[mt], acc[mt][nt]);
;       __builtin_amdgcn_sched_barrier(0);
;     }
;     ...
;   if constexpr (EPI == EPI_INPROJ) {
;     const int slot = n0 >> 9;
;     const int dbase = (slot < 4) ? slot * 512 : (slot - 1) * 512;
;     float* rsc = (float*)(lds + 73728 + 64);
;     rsc[tid] = rsqrtf(rowsum * (1.f / 1024.f) + 1e-6f);
;     __syncthreads();
; #pragma unroll
;     for (int mt = 0; mt < 8; ++mt) {
;       const int row = m0 + wm * 128 + mt * 16 + c16;
;       const float rs = rsc[wm * 128 + mt * 16 + c16];
; #pragma unroll
;       for (int nt = 0; nt < 4; ++nt) {
;         const int cc0 = (n0 & 511) + wn * 64 + nt * 16 + quad * 4;
;         float v[4];
; #pragma unroll
;         for (int r = 0; r < 4; ++r) v[r] = acc[mt][nt][r] * rs;
;         if (slot == 4) {
	ds_read_b128 v[188:191], v147 offset:40960
	ds_read_b128 v[192:195], v147 offset:41984
	ds_read_b128 v[196:199], v147 offset:43008
	ds_read_b128 v[200:203], v147 offset:44032
	ds_read_b128 v[78:81], v164 offset:24576
	ds_read_b128 v[82:85], v164 offset:25600
	s_waitcnt lgkmcnt(1)
	v_mfma_f32_16x16x32_bf16 v[204:207], v[188:191], v[78:81], v[126:129]
	v_mfma_f32_16x16x32_bf16 v[122:125], v[192:195], v[78:81], v[122:125]
	v_mfma_f32_16x16x32_bf16 v[118:121], v[196:199], v[78:81], v[118:121]
	v_mfma_f32_16x16x32_bf16 v[114:117], v[200:203], v[78:81], v[114:117]
	ds_read_b128 v[78:81], v164 offset:26624
	ds_read_b128 v[126:129], v164 offset:27648
	s_waitcnt lgkmcnt(2)
	v_mfma_f32_16x16x32_bf16 v[110:113], v[188:191], v[82:85], v[106:109]
	v_mfma_f32_16x16x32_bf16 v[106:109], v[192:195], v[82:85], v[98:101]
	v_mfma_f32_16x16x32_bf16 v[102:105], v[196:199], v[82:85], v[86:89]
	v_mfma_f32_16x16x32_bf16 v[98:101], v[200:203], v[82:85], v[74:77]
	s_waitcnt lgkmcnt(1)
	v_mfma_f32_16x16x32_bf16 v[94:97], v[188:191], v[78:81], v[70:73]
	s_waitcnt lgkmcnt(0)
	v_mfma_f32_16x16x32_bf16 v[70:73], v[196:199], v[126:129], v[46:49]
	s_nop 2
	ds_read_b128 v[46:49], v164 offset:28672
	ds_read_b128 v[208:211], v164 offset:29696
	v_mfma_f32_16x16x32_bf16 v[90:93], v[192:195], v[78:81], v[66:69]
	v_mfma_f32_16x16x32_bf16 v[86:89], v[196:199], v[78:81], v[62:65]
	v_mfma_f32_16x16x32_bf16 v[82:85], v[200:203], v[78:81], v[58:61]
	v_mfma_f32_16x16x32_bf16 v[78:81], v[188:191], v[126:129], v[54:57]
	v_mfma_f32_16x16x32_bf16 v[74:77], v[192:195], v[126:129], v[50:53]
	v_mfma_f32_16x16x32_bf16 v[66:69], v[200:203], v[126:129], v[42:45]
	s_waitcnt lgkmcnt(1)
	v_mfma_f32_16x16x32_bf16 v[62:65], v[188:191], v[46:49], v[38:41]
	s_waitcnt lgkmcnt(0)
	v_mfma_f32_16x16x32_bf16 v[38:41], v[196:199], v[208:211], v[14:17]
	s_nop 2
	ds_read_b128 v[14:17], v164 offset:30720
	ds_read_b128 v[126:129], v164 offset:31744
	v_mfma_f32_16x16x32_bf16 v[58:61], v[192:195], v[46:49], v[34:37]
	v_mfma_f32_16x16x32_bf16 v[54:57], v[196:199], v[46:49], v[30:33]
	v_mfma_f32_16x16x32_bf16 v[50:53], v[200:203], v[46:49], v[26:29]
	v_mfma_f32_16x16x32_bf16 v[46:49], v[188:191], v[208:211], v[22:25]
	v_mfma_f32_16x16x32_bf16 v[42:45], v[192:195], v[208:211], v[18:21]
	v_mfma_f32_16x16x32_bf16 v[34:37], v[200:203], v[208:211], v[10:13]
	s_waitcnt lgkmcnt(1)
	v_mfma_f32_16x16x32_bf16 v[30:33], v[188:191], v[14:17], v[6:9]
	v_mfma_f32_16x16x32_bf16 v[26:29], v[192:195], v[14:17], v[2:5]
	v_mfma_f32_16x16x32_bf16 v[22:25], v[196:199], v[14:17], v[168:171]
	v_mfma_f32_16x16x32_bf16 v[18:21], v[200:203], v[14:17], v[160:163]
	s_waitcnt lgkmcnt(0)
	v_mfma_f32_16x16x32_bf16 v[14:17], v[188:191], v[126:129], v[130:133]
	v_mfma_f32_16x16x32_bf16 v[10:13], v[192:195], v[126:129], v[134:137]
	v_mfma_f32_16x16x32_bf16 v[6:9], v[196:199], v[126:129], v[138:141]
	v_mfma_f32_16x16x32_bf16 v[2:5], v[200:203], v[126:129], v[156:159]
	v_add_f32_e32 v126, v146, v145
	v_fmamk_f32 v126, v126, 0x3a800000, v175
	s_mov_b32 s9, 0x800000
	v_mul_f32_e32 v127, 0x4b800000, v126
	v_cmp_gt_f32_e32 vcc, s9, v126
	s_and_b32 s24, s23, 0xfffffe00
	s_ashr_i32 s8, s22, 2
	v_cndmask_b32_e32 v126, v126, v127, vcc
	v_rsq_f32_e32 v126, v126
	s_add_i32 s25, s24, 0xfffffe00
	s_cmp_lt_i32 s8, 4
	s_cselect_b32 s24, s24, s25
	v_mul_f32_e32 v127, 0x45800000, v126
	v_cndmask_b32_e32 v126, v126, v127, vcc
	v_lshl_add_u32 v127, v167, 2, s64
	ds_write_b32 v127, v126
	v_and_b32_e32 v127, 0x3fffff8f, v167
	s_and_b32 s23, s23, 0x180
	s_cmp_lg_u32 s8, 4
	v_lshl_add_u32 v169, v127, 2, s64
	s_waitcnt lgkmcnt(0)
	s_barrier
	v_lshlrev_b32_e32 v128, 6, v144
	v_lshlrev_b32_e32 v0, 2, v0
	s_cselect_b64 s[36:37], -1, 0
	s_cmp_eq_u32 s8, 2
	ds_read_b32 v146, v169
	v_or3_b32 v166, v128, s23, v0
	s_cselect_b64 s[28:29], -1, 0
	s_and_b32 s23, s22, 0x1fffff8
	v_and_b32_e32 v126, 0xffffff80, v167
	s_cmp_lg_u32 s23, 8
	v_add_u32_e32 v170, s26, v126
	s_cselect_b64 s[44:45], -1, 0
	s_and_b32 s22, s22, 0x1ffffec
	v_or_b32_e32 v126, v170, v142
	s_cmp_lg_u32 s22, 4
	s_cselect_b64 s[26:27], -1, 0
	v_and_b32_e32 v168, 4, v0
	v_cmp_gt_u32_e64 s[40:41], 32, v143
	s_ashr_i32 s25, s24, 31
	v_mad_i64_i32 v[144:145], s[22:23], v126, s35, 0
	s_waitcnt lgkmcnt(0)
	v_pk_mul_f32 v[138:139], v[204:205], v[146:147] op_sel_hi:[1,0]
	v_pk_mul_f32 v[136:137], v[206:207], v[146:147] op_sel_hi:[1,0]
	s_mov_b64 s[38:39], -1
	s_and_b64 vcc, exec, s[36:37]
	s_cbranch_vccz .LBB0_200
	s_and_b64 vcc, exec, s[44:45]
	s_cbranch_vccz .LBB0_196
	s_andn2_b64 vcc, exec, s[26:27]
	s_cbranch_vccnz .LBB0_193
	s_cmp_lt_i32 s8, 8
	s_cbranch_scc1 .LBB0_187
	s_cmp_gt_i32 s8, 8
	s_cbranch_scc0 .LBB0_188
	s_cmp_eq_u32 s8, 9
	s_mov_b64 s[72:73], 0
	s_cselect_b64 s[38:39], -1, 0
	s_branch .LBB0_189

; DI int opaque_tid() { int t = threadIdx.x; asm volatile("" : "+v"(t)); return t; }
; DI void diff_attn_item(const Params& p, int layer, int qb, int bh, char* lds) {
;   const int b = bh >> 2, h = bh & 3;
;   const int tok0 = b * SEQ + qb * 64;
;   const int tid_ = opaque_tid(), lane = tid_ & 63, w = tid_ >> 6, c16 = lane & 15, quad = lane >> 4;
;   const int sidx = w & 1, g = w >> 1;
;   const bf16_t* qp = p.proj + (size_t)tok0 * PW + C_Q + h * 128;
;   const bf16_t* kp = p.proj + (size_t)b * SEQ * PW + C_K + h * 128;
;   const bf16_t* vtp = p.vt + (size_t)((b * 4 + h) * 128) * SEQ;
;   const int nkt = qb + 1;
;   bf16x8 qf[2][2];
; #pragma unroll
;   for (int qt = 0; qt < 2; ++qt)
; #pragma unroll
;     for (int ff = 0; ff < 2; ++ff)
;       qf[qt][ff] = *(const bf16x8*)(qp + (size_t)(g * 32 + qt * 16 + c16) * PW + (sidx * 2 + ff) * 32 + quad * 8);
;   float m[2], l[2];
;   f32x4 O[8][2];
; #pragma unroll
;   for (int qt = 0; qt < 2; ++qt) {
;     m[qt] = 0.f; l[qt] = 0.f;
; #pragma unroll
;     for (int d = 0; d < 8; ++d) O[d][qt] = f32x4{0.f, 0.f, 0.f, 0.f};
;   }
;   const int prow = lane >> 3, pch = lane & 7;
;   unsigned koff[4], voff[4];
; #pragma unroll
;   for (int i = 0; i < 4; ++i) {
;     const int pi = w * 4 + i;
;     { const int row = (pi & 7) * 8 + prow, sub = pi >> 3, c = pch ^ ((row >> 1) & 7);
;       koff[i] = (unsigned)((row * PW + sub * 64 + c * 8) * 2); }
;     { const int row = pi * 8 + prow, c = pch ^ ((row >> 1) & 7);
;       voff[i] = (unsigned)((row * SEQ + c * 8) * 2); }
;   }
;   auto gload = [&](int kt, int buf) {
;     char* base = lds + buf * 32768;
;     const char* kt_base = (const char*)(kp + (size_t)kt * 64 * PW);
;     const char* vt_base = (const char*)(vtp + (size_t)kt * 64);
; #pragma unroll
;     for (int i = 0; i < 4; ++i)
;       __builtin_amdgcn_global_load_lds((const unsigned*)(kt_base + koff[i]), (unsigned*)(base + (w * 4 + i) * 1024 + lane * 16), 16, 0, 0);
; #pragma unroll
;     for (int i = 0; i < 4; ++i)
;       __builtin_amdgcn_global_load_lds((const unsigned*)(vt_base + voff[i]), (unsigned*)(base + 16384 + (w * 4 + i) * 1024 + lane * 16), 16, 0, 0);
;   };
;   const int qw0 = qb * 64 + g * 32;
;   gload(0, 0); __syncthreads();
;   for (int kt = 0; kt < nkt; ++kt) {
;     if (kt + 1 < nkt) gload(kt + 1, (kt + 1) & 1);
.LBB0_1259:
	s_or_b64 exec, exec, s[0:1]
	v_mov_b32_e32 v0, s3
	s_waitcnt lgkmcnt(0)
	s_barrier
	ds_read_b32 v0, v0
	s_movk_i32 s0, 0xff
	s_waitcnt lgkmcnt(0)
	v_cmp_lt_i32_e32 vcc, s0, v0
	v_readfirstlane_b32 s5, v0
	s_mov_b64 s[0:1], -1
	s_cbranch_vccnz .LBB0_1254
	s_ashr_i32 s34, s5, 1
	s_sub_i32 s23, 0x7f, s34
	s_and_b32 s8, s5, 1
	v_readlane_b32 s0, v228, 20
	s_or_b32 s6, s8, s0
	s_lshl_b32 s5, s23, 6
	v_readlane_b32 s0, v228, 21
	s_add_i32 s41, s5, s0
	s_mul_i32 s1, s41, 0x2400
	s_mul_hi_u32 s0, s41, 0x2400
	s_add_u32 s1, s78, s1
	s_addc_u32 s7, s79, s0
	s_lshl_b32 s0, s6, 7
	s_and_b32 s0, s0, 0x180
	v_mov_b32_e32 v17, v172
	s_lshl_b32 s64, s0, 1
	s_add_u32 s0, s1, s64
	v_ashrrev_i32_e32 v193, 7, v17
	v_ashrrev_i32_e32 v86, 6, v17
	v_and_b32_e32 v189, 15, v17
	s_addc_u32 s1, s7, 0
	v_lshlrev_b32_e32 v190, 5, v193
	v_and_b32_e32 v84, 48, v17
	v_mov_b32_e32 v85, v1
	v_and_b32_e32 v194, 1, v86
	v_or_b32_e32 v6, v190, v189
	v_lshl_add_u64 v[2:3], s[0:1], 0, v[84:85]
	v_mad_i64_i32 v[4:5], s[0:1], v6, s35, v[2:3]
	v_lshlrev_b32_e32 v0, 7, v194
	v_lshl_add_u64 v[4:5], v[4:5], 0, v[0:1]
	global_load_dwordx4 v[36:39], v[4:5], off offset:2048
	global_load_dwordx4 v[40:43], v[4:5], off offset:2112
	v_or_b32_e32 v4, 16, v6
	v_mad_i64_i32 v[2:3], s[0:1], v4, s35, v[2:3]
	v_lshl_add_u64 v[2:3], v[2:3], 0, v[0:1]
	v_readlane_b32 s0, v228, 22
	v_bfe_u32 v16, v17, 4, 2
	global_load_dwordx4 v[44:47], v[2:3], off offset:2048
	global_load_dwordx4 v[48:51], v[2:3], off offset:2112
	s_add_u32 s36, s0, s64
	v_readlane_b32 s0, v228, 23
	v_bfe_u32 v90, v17, 3, 3
	v_lshlrev_b32_e32 v3, 5, v86
	s_addc_u32 s37, s0, 0
	v_and_b32_e32 v5, 0xffffffc0, v3
	v_and_or_b32 v0, v3, 32, v90
	v_xor_b32_e32 v2, v16, v17
	s_movk_i32 s0, 0x1200
	v_mad_u32_u24 v85, v0, s0, v5
	v_lshlrev_b32_e32 v0, 3, v2
	v_or_b32_e32 v2, v3, v90
	v_lshlrev_b32_e32 v96, 4, v17
	v_lshlrev_b32_e32 v2, 14, v2
	v_and_b32_e32 v4, 0x70, v96
	v_bitop3_b32 v6, v2, v4, v84 bitop3:0xf6
	v_or_b32_e32 v4, 8, v3
	v_and_or_b32 v2, v4, 40, v90
	v_lshrrev_b32_e32 v7, 1, v2
	v_xor_b32_e32 v7, v7, v17
	v_or_b32_e32 v4, v4, v90
	v_mad_u32_u24 v88, v2, s0, v5
	v_lshlrev_b32_e32 v2, 3, v7
	v_lshrrev_b32_e32 v7, 1, v4
	v_xor_b32_e32 v7, v7, v17
	v_lshlrev_b32_e32 v7, 4, v7
	v_and_b32_e32 v92, 0x70, v7
	v_or_b32_e32 v7, 16, v3
	v_lshl_or_b32 v10, v4, 14, v92
	v_and_or_b32 v4, v7, 48, v90
	v_or_b32_e32 v7, v7, v90
	v_lshrrev_b32_e32 v8, 1, v7
	v_xor_b32_e32 v8, v8, v17
	v_lshlrev_b32_e32 v8, 4, v8
	v_and_b32_e32 v93, 0x70, v8
	v_or_b32_e32 v3, 24, v3
	v_lshl_or_b32 v12, v7, 14, v93
	v_and_or_b32 v7, v3, 56, v90
	v_lshrrev_b32_e32 v8, 1, v7
	v_xor_b32_e32 v8, v8, v17
	v_mad_u32_u24 v91, v4, s0, v5
	v_mad_u32_u24 v94, v7, s0, v5
	v_lshlrev_b32_e32 v5, 3, v8
	v_and_b32_e32 v95, 56, v5
	v_or_b32_e32 v5, v95, v94
	v_or_b32_e32 v3, v3, v90
	v_lshlrev_b32_e32 v8, 1, v5
	v_lshrrev_b32_e32 v5, 1, v3
	v_xor_b32_e32 v5, v5, v17
	v_lshlrev_b32_e32 v5, 4, v5
	v_and_b32_e32 v191, 63, v17
	v_and_b32_e32 v87, 56, v0
	v_and_b32_e32 v97, 0x70, v5
	v_or_b32_e32 v0, v85, v87
	v_lshl_or_b32 v14, v3, 14, v97
	v_lshlrev_b32_e32 v3, 12, v86
	v_lshlrev_b32_e32 v5, 4, v191
	v_lshlrev_b32_e32 v0, 1, v0
	v_and_b32_e32 v89, 56, v2
	v_add3_u32 v195, 16, v3, v5
	v_or_b32_e32 v2, v89, v88
	s_lshl_b32 s0, s6, 21
	v_lshl_add_u64 v[18:19], s[36:37], 0, v[0:1]
	s_mov_b64 s[10:11], 0xc00
	v_readfirstlane_b32 s6, v195
	v_readfirstlane_b32 s101, v195
	v_lshlrev_b32_e32 v2, 1, v2
	v_lshl_add_u64 v[18:19], v[18:19], 0, s[10:11]
	s_mov_b32 m0, s6
	v_mov_b32_e32 v3, v1
	v_add_u32_e32 v5, 0x400, v195
	v_or_b32_e32 v4, v91, v87
	global_load_lds_dwordx4 v[18:19], off
	v_lshl_add_u64 v[18:19], s[36:37], 0, v[2:3]
	v_readfirstlane_b32 s6, v5
	v_lshlrev_b32_e32 v4, 1, v4
	v_lshl_add_u64 v[18:19], v[18:19], 0, s[10:11]
	s_mov_b32 m0, s6
	v_mov_b32_e32 v5, v1
	v_add_u32_e32 v7, 0x800, v195
	global_load_lds_dwordx4 v[18:19], off
	v_lshl_add_u64 v[18:19], s[36:37], 0, v[4:5]
	v_readfirstlane_b32 s6, v7
	v_lshl_add_u64 v[18:19], v[18:19], 0, s[10:11]
	s_mov_b32 m0, s6
	v_mov_b32_e32 v9, v1
	v_add_u32_e32 v7, 0xc00, v195
	global_load_lds_dwordx4 v[18:19], off
	v_lshl_add_u64 v[18:19], s[36:37], 0, v[8:9]
	v_readfirstlane_b32 s6, v7
	v_add_u32_e32 v7, 0x4000, v195
	s_add_u32 s0, s48, s0
	v_lshl_add_u64 v[18:19], v[18:19], 0, s[10:11]
	s_mov_b32 m0, s6
	v_readfirstlane_b32 s6, v7
	v_add_u32_e32 v7, 0x4400, v195
	s_addc_u32 s1, s49, 0
	global_load_lds_dwordx4 v[18:19], off
	s_mov_b32 m0, s6
	v_readfirstlane_b32 s6, v7
	v_add_u32_e32 v7, 0x4800, v195
	global_load_lds_dwordx4 v6, s[0:1]
	s_mov_b32 m0, s6
	v_readfirstlane_b32 s6, v7
	v_add_u32_e32 v7, 0x4c00, v195
	global_load_lds_dwordx4 v10, s[0:1]
	s_mov_b32 m0, s6
	v_readfirstlane_b32 s6, v7
	global_load_lds_dwordx4 v12, s[0:1]
	s_mov_b32 m0, s6
	s_cmpk_lg_i32 s34, 0x7f
	global_load_lds_dwordx4 v14, s[0:1]
	s_cselect_b64 s[44:45], -1, 0
	s_cmpk_eq_i32 s34, 0x7f
	s_waitcnt vmcnt(0) lgkmcnt(0)
	s_barrier
	s_cbranch_scc1 .LBB0_1262
	v_mov_b32_e32 v7, v1
	v_mov_b32_e32 v11, v1
	v_mov_b32_e32 v13, v1
	v_mov_b32_e32 v15, v1
	v_lshl_add_u64 v[6:7], s[0:1], 0, v[6:7]
	v_lshl_add_u64 v[10:11], s[0:1], 0, v[10:11]
	v_lshl_add_u64 v[12:13], s[0:1], 0, v[12:13]
	v_lshl_add_u64 v[14:15], s[0:1], 0, v[14:15]
	s_add_u32 s0, s36, 0x90c00
	s_addc_u32 s1, s37, 0
	v_lshl_add_u64 v[18:19], s[0:1], 0, v[0:1]
	v_add_u32_e32 v0, 0x8000, v195
	v_lshl_add_u64 v[2:3], s[0:1], 0, v[2:3]
	v_readfirstlane_b32 s6, v0
	v_add_u32_e32 v0, 0x8400, v195
	s_mov_b32 m0, s6
	v_readfirstlane_b32 s6, v0
	v_add_u32_e32 v0, 0x8800, v195
	global_load_lds_dwordx4 v[18:19], off
	s_mov_b32 m0, s6
	v_readfirstlane_b32 s6, v0
	global_load_lds_dwordx4 v[2:3], off
	v_lshl_add_u64 v[2:3], s[0:1], 0, v[4:5]
	s_mov_b32 m0, s6
	v_add_u32_e32 v0, 0x8c00, v195
	global_load_lds_dwordx4 v[2:3], off
	v_lshl_add_u64 v[2:3], s[0:1], 0, v[8:9]
	v_readfirstlane_b32 s0, v0
	v_add_u32_e32 v0, 0xc000, v195
	s_mov_b32 m0, s0
	v_readfirstlane_b32 s0, v0
	v_add_u32_e32 v0, 0xc400, v195
	global_load_lds_dwordx4 v[2:3], off
	v_lshl_add_u64 v[2:3], v[6:7], 0, s[70:71]
	s_mov_b32 m0, s0
	v_readfirstlane_b32 s0, v0
	v_add_u32_e32 v0, 0xc800, v195
	global_load_lds_dwordx4 v[2:3], off
	v_lshl_add_u64 v[2:3], v[10:11], 0, s[70:71]
	s_mov_b32 m0, s0
	v_readfirstlane_b32 s0, v0
	v_add_u32_e32 v0, 0xcc00, v195
	global_load_lds_dwordx4 v[2:3], off
	v_lshl_add_u64 v[2:3], v[12:13], 0, s[70:71]
	s_mov_b32 m0, s0
	v_readfirstlane_b32 s0, v0
	global_load_lds_dwordx4 v[2:3], off
	v_lshl_add_u64 v[2:3], v[14:15], 0, s[70:71]
	s_mov_b32 m0, s0
	s_nop 0
	global_load_lds_dwordx4 v[2:3], off

; DI void diff_attn_item(const Params& p, int layer, int qb, int bh, char* lds) {
;     ...
;   auto gload = [&](int kt, int buf) {
;     char* base = lds + buf * 32768;
;     const char* kt_base = (const char*)(kp + (size_t)kt * 64 * PW);
;     const char* vt_base = (const char*)(vtp + (size_t)kt * 64);
; #pragma unroll
;     for (int i = 0; i < 4; ++i)
;       __builtin_amdgcn_global_load_lds((const unsigned*)(kt_base + koff[i]), (unsigned*)(base + (w * 4 + i) * 1024 + lane * 16), 16, 0, 0);
; #pragma unroll
;     for (int i = 0; i < 4; ++i)
;       __builtin_amdgcn_global_load_lds((const unsigned*)(vt_base + voff[i]), (unsigned*)(base + 16384 + (w * 4 + i) * 1024 + lane * 16), 16, 0, 0);
;   };
;   const int qw0 = qb * 64 + g * 32;
;   gload(0, 0); __syncthreads();
;   for (int kt = 0; kt < nkt; ++kt) {
;     if (kt + 1 < nkt) gload(kt + 1, (kt + 1) & 1);
.LBB0_1270:
	s_add_i32 s0, s34, 0x80
	s_cmp_ge_u32 s0, s23
	s_cbranch_scc1 .LBB0_1272
	s_add_i32 s0, s39, 0x8000
	s_and_b32 s0, s0, 0x8000
	s_add_i32 s0, s0, s101
	s_mov_b32 m0, s0
	s_nop 0
	global_load_lds_dwordx4 v170, s[36:37]
	s_add_i32 m0, s0, 0x400
	s_nop 0
	global_load_lds_dwordx4 v168, s[36:37]
	s_add_i32 m0, s0, 0x800
	s_nop 0
	global_load_lds_dwordx4 v166, s[36:37]
	s_add_i32 m0, s0, 0xc00
	s_nop 0
	global_load_lds_dwordx4 v164, s[36:37]
	s_add_i32 m0, s0, 0x4000
	s_nop 0
	global_load_lds_dwordx4 v0, s[6:7]
	s_add_i32 m0, s0, 0x4400
	s_nop 0
	global_load_lds_dwordx4 v2, s[6:7]
	s_add_i32 m0, s0, 0x4800
	s_nop 0
	global_load_lds_dwordx4 v160, s[6:7]
	s_add_i32 m0, s0, 0x4c00
	s_nop 0
	global_load_lds_dwordx4 v162, s[6:7]
